# scan pass 1 prep stage: lora fragment reads issued ahead behind counted LDS waits
# baseline (speedup 1.0000x reference)
; #define LAS __attribute__((address_space(3)))
; #define MFMA32(a, b, c) __builtin_amdgcn_mfma_f32_32x32x16_bf16((a), (b), (c), 0, 0, 0)
; __device__ __forceinline__ void scan_pass1(const ScanP& sp, int b, int h, int seg, LAS unsigned char* lds) {
;     ...
;             {
;                 const int l5_ = lane & 31, h5_ = lane >> 5;
;                 const LAS unsigned char* arow = lds + O_LORA + ((4 * w + (l5_ & 3)) * 72 + h5_ * 8) * 2;
; #pragma unroll
;                 for (int lo_ = 0; lo_ < 2; ++lo_)
; #pragma unroll
;                     for (int jb_ = 0; jb_ < 2; ++jb_) {
;                         f32x16 D_;
; #pragma unroll
;                         for (int i = 0; i < 16; ++i) D_[i] = 0.f;
; #pragma unroll
;                         for (int ks = 0; ks < 2; ++ks)
;                             D_ = MFMA32(*(const LAS bf16x8*)(arow + (lo_ * 32 + ks * 16) * 2), *(const LAS bf16x8*)(lds + O_WUP + lo_ * 5120 + ((32 * jb_ + l5_) * 40 + ks * 16 + h5_ * 8) * 2), D_);
;                         if (h5_ == 0) {
;                             LAS float* dst_ = (lo_ == 0 ? yb : qb) + (w * 4) * 64 + 32 * jb_ + l5_;
;                             dst_[0] = D_[0]; dst_[64] = D_[1]; dst_[128] = D_[2]; dst_[192] = D_[3];
;                         }
;                     }
.LBB0_291:
	s_waitcnt lgkmcnt(0)
	ds_read_b128 v[112:115], v185 offset:16384
	ds_read_b128 v[68:71], v186
	ds_read_b128 v[116:119], v185 offset:16416
	ds_read_b128 v[130:133], v186 offset:32
	ds_read_b128 v[238:241], v186 offset:2560
	ds_read_b128 v[242:245], v186 offset:2592
	ds_read_b128 v[230:233], v185 offset:16448
	ds_read_b128 v[234:237], v185 offset:16480
	ds_read_b128 v[246:249], v186 offset:5120
	s_waitcnt lgkmcnt(7)
	v_mfma_f32_32x32x16_bf16 v[68:83], v[112:115], v[68:71], 0
	s_waitcnt lgkmcnt(5)
	v_mfma_f32_32x32x16_bf16 v[68:83], v[116:119], v[130:133], v[68:83]
	s_mov_b64 s[0:1], exec
	s_and_b64 exec, exec, s[8:9]
	s_nop 9
	ds_write2st64_b32 v181, v68, v69 offset1:1
	ds_write2st64_b32 v181, v70, v71 offset0:2 offset1:3
	s_mov_b64 exec, s[0:1]
	ds_read_b128 v[130:133], v186 offset:5152
	s_waitcnt lgkmcnt(7)
	v_mfma_f32_32x32x16_bf16 v[68:83], v[112:115], v[238:241], 0
	s_waitcnt lgkmcnt(6)
	v_mfma_f32_32x32x16_bf16 v[68:83], v[116:119], v[242:245], v[68:83]
	s_mov_b64 s[0:1], exec
	s_and_b64 exec, exec, s[8:9]
	s_nop 9
	ds_write2_b32 v181, v68, v69 offset0:32 offset1:96
	ds_write2_b32 v181, v70, v71 offset0:160 offset1:224
	s_mov_b64 exec, s[0:1]
	ds_read_b128 v[112:115], v186 offset:7680
	ds_read_b128 v[116:119], v186 offset:7712
	s_waitcnt lgkmcnt(7)
	v_mfma_f32_32x32x16_bf16 v[68:83], v[230:233], v[246:249], 0
	s_waitcnt lgkmcnt(4)
	v_mfma_f32_32x32x16_bf16 v[68:83], v[234:237], v[130:133], v[68:83]
	s_mov_b64 s[0:1], exec
	s_and_b64 exec, exec, s[8:9]
	s_nop 9
	ds_write2st64_b32 v182, v68, v69 offset1:1
	ds_write2st64_b32 v182, v70, v71 offset0:2 offset1:3
	s_mov_b64 exec, s[0:1]
	s_waitcnt lgkmcnt(3)
	v_mfma_f32_32x32x16_bf16 v[68:83], v[230:233], v[112:115], 0
	s_waitcnt lgkmcnt(2)
	v_mfma_f32_32x32x16_bf16 v[68:83], v[234:237], v[116:119], v[68:83]
	s_mov_b64 s[0:1], exec
	s_and_b64 exec, exec, s[8:9]
	s_nop 9
	ds_write2_b32 v182, v68, v69 offset0:32 offset1:96
	ds_write2_b32 v182, v70, v71 offset0:160 offset1:224
